# NSA stream even steps: next-tile LDS store + prefetch moved from step top to step end
# speedup vs baseline: 1.0123x; 1.0123x over previous
.LBB0_712:
	s_lshl_b32 s6, s3, 14
	s_and_b32 s8, s6, 0x4000
	s_add_i32 s6, s81, -3
	s_cmp_lt_u32 s6, s1
	s_cselect_b64 s[40:41], -1, 0
.LBB0_716:
	s_add_i32 s70, s80, s81
	s_cmpk_eq_i32 s70, 0x44
	s_cselect_b64 s[68:69], -1, 0
	s_cmpk_lg_i32 s70, 0x44
	s_cbranch_scc1 .LBB0_720
	s_waitcnt lgkmcnt(0)
	v_mov_b32_e32 v48, v230
	s_nop 1
	v_permlane32_swap_b32_e32 v230, v48
	s_and_saveexec_b64 s[6:7], s[4:5]
	s_cbranch_execz .LBB0_719
	v_add_f32_e32 v48, v230, v48
	v_div_scale_f32 v49, s[10:11], v48, v48, v197
	v_rcp_f32_e32 v50, v49
	v_div_scale_f32 v51, vcc, v197, v48, v197
	v_fma_f32 v52, -v49, v50, 1.0
	v_fmac_f32_e32 v50, v52, v50
	v_mul_f32_e32 v52, v51, v50
	v_fma_f32 v53, -v49, v52, v51
	v_fmac_f32_e32 v52, v53, v50
	v_fma_f32 v49, -v49, v52, v51
	v_div_fmas_f32 v49, v49, v50, v52
	v_div_fixup_f32 v48, v49, v48, v197
	ds_write_b32 v184, v48

.LBB0_746:
	s_andn2_b64 vcc, exec, s[40:41]
	s_cbranch_vccnz .Lnsa_e1_nostore
	s_lshl_b32 s9, s3, 14
	s_and_b32 s9, s9, 0x4000
	s_xor_b32 s6, s9, 0x4000
	s_add_i32 s6, s6, 0x10000
	v_add3_u32 v64, s6, v173, v174
	v_add3_u32 v65, s6, v175, v176
	v_add3_u32 v65, v65, v177, v178
	s_waitcnt vmcnt(1)
	ds_write_b128 v64, v[144:147]
	s_waitcnt vmcnt(0)
	ds_write_b128 v65, v[152:155] offset:8192
.Lnsa_e1_nostore:
	s_add_i32 s6, s81, -1
	s_cmp_ge_u32 s6, s1
	s_cbranch_scc1 .Lnsa_e1_noload
	s_cmp_gt_u32 s6, s93
	s_cselect_b64 s[6:7], -1, 0
	s_and_b64 s[6:7], s[6:7], exec
	s_cselect_b32 s9, s79, 0
	s_cselect_b32 s72, s33, 0x700
	s_cselect_b32 s6, 0x800, s92
	s_add_i32 s9, s9, s81
	s_lshl_b32 s9, s9, 6
	s_sub_i32 s9, s9, 64
	s_mov_b32 s7, s73
	v_mad_i64_i32 v[64:65], s[10:11], s9, v172, v[166:167]
	v_lshl_add_u64 v[66:67], v[64:65], 0, s[6:7]
	v_lshl_add_u64 v[64:65], v[64:65], 0, s[72:73]
	global_load_dwordx4 v[144:147], v[66:67], off
	global_load_dwordx4 v[152:155], v[64:65], off
.Lnsa_e1_noload:
	s_andn2_b64 vcc, exec, s[40:41]
	s_add_i32 s6, s3, 1
	s_waitcnt lgkmcnt(0)
	s_barrier
	s_cbranch_vccnz .LBB0_750
	s_lshl_b32 s6, s6, 14
	s_and_b32 s8, s6, 0x4000
	s_cmp_ge_u32 s71, s78
	s_cbranch_scc0 .LBB0_751
	s_cmp_ge_u32 s81, s1
	s_cbranch_scc0 .LBB0_752
